# P4 epilogue start: counted vmcnt waits in front of the first use of each input-row load instead of one vmcnt(0) behind all 14 operand loads
# speedup vs baseline: 1.0025x; 1.0025x over previous
.LBB0_464:
	s_lshl_b32 s6, s62, 7
	v_mov_b32_e32 v239, v224
	v_mov_b32_e32 v237, v225
	s_or_b32 s6, s6, s96
	s_nop 0
	v_lshl_add_u32 v238, v237, 3, s6
	s_lshl_b32 s6, s63, 8
	s_add_i32 s6, s6, s16
	v_lshl_add_u32 v171, v239, 3, s6
	v_lshlrev_b32_e32 v232, 1, v238
	v_lshlrev_b32_e32 v233, 11, v171
	v_lshlrev_b32_e32 v92, 2, v238
	v_add_u32_e32 v164, v233, v232
	v_or_b32_e32 v235, 0x1000, v233
	global_load_dwordx4 v[184:187], v92, s[2:3] offset:16
	global_load_dwordx4 v[188:191], v92, s[2:3]
	global_load_dwordx4 v[192:195], v92, s[12:13] offset:16
	global_load_dwordx4 v[196:199], v92, s[12:13]
	global_load_dwordx4 v[240:243], v92, s[36:37] offset:16
	global_load_dwordx4 v[200:203], v92, s[36:37]
	v_or_b32_e32 v234, 0x800, v233
	v_add_u32_e32 v180, v235, v232
	v_or_b32_e32 v236, 0x1800, v233
	v_add_u32_e32 v176, 0x2000, v164
	v_add_u32_e32 v172, 0x3000, v164
	v_add_u32_e32 v182, v234, v232
	global_load_dwordx4 v[244:247], v164, s[26:27]
	global_load_dwordx4 v[152:155], v182, s[26:27]
	v_add_u32_e32 v178, v236, v232
	global_load_dwordx4 v[148:151], v180, s[26:27]
	global_load_dwordx4 v[144:147], v178, s[26:27]
	v_add_u32_e32 v174, 0x2800, v164
	global_load_dwordx4 v[140:143], v176, s[26:27]
	global_load_dwordx4 v[132:135], v174, s[26:27]
	v_add_u32_e32 v170, 0x3800, v164
	global_load_dwordx4 v[112:115], v172, s[26:27]
	global_load_dwordx4 v[92:95], v170, s[26:27]
	v_and_b32_e32 v171, 0x1ff8, v171
	s_waitcnt vmcnt(8)
	v_pk_mul_f32 v[204:205], v[186:187], s[48:49] op_sel_hi:[1,0]
	v_pk_mul_f32 v[216:217], v[190:191], s[48:49] op_sel_hi:[1,0]
	v_pk_mul_f32 v[222:223], v[188:189], s[48:49] op_sel_hi:[1,0]
	v_pk_mul_f32 v[214:215], v[198:199], s[48:49] op_sel_hi:[1,0]
	v_pk_mul_f32 v[220:221], v[196:197], s[48:49] op_sel_hi:[1,0]
	v_pk_mul_f32 v[212:213], v[202:203], s[50:51] op_sel_hi:[1,0]
	v_pk_mul_f32 v[218:219], v[200:201], s[50:51] op_sel_hi:[1,0]
	v_pk_mul_f32 v[202:203], v[194:195], s[48:49] op_sel_hi:[1,0]
	v_pk_mul_f32 v[200:201], v[242:243], s[50:51] op_sel_hi:[1,0]
	v_pk_mul_f32 v[210:211], v[184:185], s[48:49] op_sel_hi:[1,0]
	v_pk_mul_f32 v[208:209], v[192:193], s[48:49] op_sel_hi:[1,0]
	v_pk_mul_f32 v[206:207], v[240:241], s[50:51] op_sel_hi:[1,0]
	v_fmamk_f32 v136, v136, 0xbfb8aa3b, v222
	v_exp_f32_e32 v136, v136
	v_fmamk_f32 v128, v128, 0xbfb8aa3b, v220
	v_fmamk_f32 v137, v137, 0xbfb8aa3b, v223
	v_exp_f32_e32 v128, v128
	v_add_f32_e32 v136, 1.0, v136
	v_rcp_f32_e32 v136, v136
	v_exp_f32_e32 v137, v137
	v_add_f32_e32 v128, 1.0, v128
	v_rcp_f32_e32 v128, v128
	v_mul_f32_e32 v136, v218, v136
	v_exp_f32_e32 v136, v136
	v_add_f32_e32 v137, 1.0, v137
	v_rcp_f32_e32 v175, v137
	v_cmp_eq_u32_e32 vcc, 0, v171
	v_fma_f32 v173, -v136, v136, 1.0
	v_sqrt_f32_e32 v173, v173
	v_fmamk_f32 v129, v129, 0xbfb8aa3b, v221
	v_exp_f32_e32 v129, v129
	s_waitcnt vmcnt(7)
	v_lshlrev_b32_e32 v185, 16, v244
	v_cndmask_b32_e64 v137, v173, 1.0, vcc
	v_mul_f32_e32 v137, v128, v137
	v_mul_f32_e32 v128, v219, v175
	v_exp_f32_e32 v128, v128
	v_and_b32_e32 v187, 0xffff0000, v244
	v_mov_b32_e32 v184, v165
	v_mul_f32_e32 v186, v137, v185
	v_fma_f32 v171, -v128, v128, 1.0
	v_sqrt_f32_e32 v171, v171
	v_add_f32_e32 v129, 1.0, v129
	v_fmamk_f32 v138, v138, 0xbfb8aa3b, v216
	v_pk_fma_f32 v[184:185], v[136:137], v[184:185], v[186:187] op_sel_hi:[1,1,0]
	v_rcp_f32_e32 v129, v129
	v_cndmask_b32_e64 v137, v171, 1.0, vcc
	v_exp_f32_e32 v171, v138
	v_fmamk_f32 v130, v130, 0xbfb8aa3b, v214
	v_mul_f32_e32 v129, v129, v137
	v_exp_f32_e32 v130, v130
	v_add_f32_e32 v137, 1.0, v171
	v_rcp_f32_e32 v137, v137
	v_mov_b32_e32 v186, v165
	v_mul_f32_e32 v138, v129, v187
	v_pk_fma_f32 v[186:187], v[128:129], v[186:187], v[138:139] op_sel_hi:[1,1,0]
	v_mul_f32_e32 v129, v212, v137
	v_exp_f32_e32 v138, v129
	v_add_f32_e32 v129, 1.0, v130
	v_fmamk_f32 v130, v139, 0xbfb8aa3b, v217
	v_exp_f32_e32 v130, v130
	v_fma_f32 v137, -v138, v138, 1.0
	v_sqrt_f32_e32 v137, v137
	v_rcp_f32_e32 v129, v129
	v_add_f32_e32 v130, 1.0, v130
	v_rcp_f32_e32 v130, v130
	v_cndmask_b32_e64 v137, v137, 1.0, vcc
	v_mul_f32_e32 v139, v129, v137
	v_fmamk_f32 v124, v124, 0xbfb8aa3b, v210
	v_mul_f32_e32 v129, v213, v130
	v_exp_f32_e32 v130, v129
	v_fmamk_f32 v129, v131, 0xbfb8aa3b, v215
	v_exp_f32_e32 v129, v129
	v_exp_f32_e32 v137, v124
	v_fma_f32 v131, -v130, v130, 1.0
	v_sqrt_f32_e32 v131, v131
	v_add_f32_e32 v129, 1.0, v129
	v_rcp_f32_e32 v129, v129
	v_lshlrev_b32_e32 v189, 16, v245
	v_cndmask_b32_e64 v131, v131, 1.0, vcc
	v_and_b32_e32 v191, 0xffff0000, v245
	v_mul_f32_e32 v131, v129, v131
	v_add_f32_e32 v129, 1.0, v137
	v_rcp_f32_e32 v129, v129
	v_mov_b32_e32 v188, v165
	v_mul_f32_e32 v190, v139, v189
	v_pk_fma_f32 v[188:189], v[138:139], v[188:189], v[190:191] op_sel_hi:[1,1,0]
	v_mov_b32_e32 v190, v165
	v_mul_f32_e32 v124, v131, v191
	v_pk_fma_f32 v[190:191], v[130:131], v[190:191], v[124:125] op_sel_hi:[1,1,0]
	v_mul_f32_e32 v124, v206, v129
	v_fmamk_f32 v120, v120, 0xbfb8aa3b, v208
	v_exp_f32_e32 v124, v124
	v_fmamk_f32 v125, v125, 0xbfb8aa3b, v211
	v_exp_f32_e32 v120, v120
	v_exp_f32_e32 v125, v125
	v_fma_f32 v129, -v124, v124, 1.0
	v_sqrt_f32_e32 v129, v129
	v_add_f32_e32 v120, 1.0, v120
	v_add_f32_e32 v125, 1.0, v125
	v_rcp_f32_e32 v120, v120
	v_rcp_f32_e32 v131, v125
	v_cndmask_b32_e64 v125, v129, 1.0, vcc
	v_fmamk_f32 v121, v121, 0xbfb8aa3b, v209
	v_mul_f32_e32 v125, v120, v125
	v_mul_f32_e32 v120, v207, v131
	v_exp_f32_e32 v120, v120
	v_exp_f32_e32 v121, v121
	v_lshlrev_b32_e32 v193, 16, v246
	v_and_b32_e32 v195, 0xffff0000, v246
	v_fma_f32 v129, -v120, v120, 1.0
	v_sqrt_f32_e32 v129, v129
	v_mov_b32_e32 v192, v165
	v_mul_f32_e32 v194, v125, v193
	v_add_f32_e32 v121, 1.0, v121
	v_fmamk_f32 v126, v126, 0xbfb8aa3b, v204
	v_pk_fma_f32 v[192:193], v[124:125], v[192:193], v[194:195] op_sel_hi:[1,1,0]
	v_rcp_f32_e32 v121, v121
	v_cndmask_b32_e64 v125, v129, 1.0, vcc
	v_exp_f32_e32 v129, v126
	v_mov_b32_e32 v194, v165
	v_mul_f32_e32 v121, v121, v125
	v_mul_f32_e32 v126, v121, v195
	v_add_f32_e32 v125, 1.0, v129
	v_rcp_f32_e32 v125, v125
	v_pk_fma_f32 v[194:195], v[120:121], v[194:195], v[126:127] op_sel_hi:[1,1,0]
	v_fmamk_f32 v122, v122, 0xbfb8aa3b, v202
	v_exp_f32_e32 v129, v122
	v_mul_f32_e32 v121, v200, v125
	v_fmamk_f32 v125, v127, 0xbfb8aa3b, v205
	v_exp_f32_e32 v125, v125
	v_exp_f32_e32 v122, v121
	v_fmamk_f32 v123, v123, 0xbfb8aa3b, v203
	v_add_f32_e32 v121, 1.0, v129
	v_add_f32_e32 v125, 1.0, v125
	v_fma_f32 v126, -v122, v122, 1.0
	v_rcp_f32_e32 v125, v125
	v_sqrt_f32_e32 v126, v126
	v_exp_f32_e32 v129, v123
	v_rcp_f32_e32 v121, v121
	v_mul_f32_e32 v123, v201, v125
	v_cndmask_b32_e64 v127, v126, 1.0, vcc
	v_exp_f32_e32 v126, v123
	v_mul_f32_e32 v123, v121, v127
	v_add_f32_e32 v121, 1.0, v129
	v_rcp_f32_e32 v121, v121
	v_fma_f32 v125, -v126, v126, 1.0
	v_sqrt_f32_e32 v125, v125
	v_lshlrev_b32_e32 v197, 16, v247
	v_and_b32_e32 v199, 0xffff0000, v247
	v_mov_b32_e32 v196, v165
	v_mul_f32_e32 v198, v123, v197
	v_pk_fma_f32 v[196:197], v[122:123], v[196:197], v[198:199] op_sel_hi:[1,1,0]
	v_cndmask_b32_e64 v123, v125, 1.0, vcc
	v_mul_f32_e32 v127, v121, v123
	v_mov_b32_e32 v198, v165
	v_mul_f32_e32 v240, v127, v199
	v_pk_fma_f32 v[198:199], v[126:127], v[198:199], v[240:241] op_sel_hi:[1,1,0]
	v_fmamk_f32 v116, v116, 0xbfb8aa3b, v222
	v_exp_f32_e32 v116, v116
	v_fmamk_f32 v108, v108, 0xbfb8aa3b, v220
	v_exp_f32_e32 v108, v108
	v_fmamk_f32 v117, v117, 0xbfb8aa3b, v223
	v_add_f32_e32 v116, 1.0, v116
	v_rcp_f32_e32 v116, v116
	v_add_f32_e32 v108, 1.0, v108
	v_rcp_f32_e32 v108, v108
	v_exp_f32_e32 v121, v117
	v_mul_f32_e32 v116, v218, v116
	v_exp_f32_e32 v241, v116
	v_fmamk_f32 v109, v109, 0xbfb8aa3b, v221
	v_exp_f32_e32 v123, v109
	s_waitcnt vmcnt(6)
	v_lshlrev_b32_e32 v242, 16, v153
	v_fma_f32 v116, -v241, v241, 1.0
	v_sqrt_f32_e32 v116, v116
	v_and_b32_e32 v244, 0xffff0000, v153
	v_lshlrev_b32_e32 v240, 16, v152
	v_mov_b32_e32 v117, v184
	v_mul_f32_e32 v116, v108, v116
	v_add_f32_e32 v108, 1.0, v121
	v_rcp_f32_e32 v121, v108
	v_mul_f32_e32 v108, v184, v241
	v_fmamk_f32 v110, v110, 0xbfb8aa3b, v214
	v_exp_f32_e32 v110, v110
	v_mul_f32_e32 v109, v219, v121
	v_exp_f32_e32 v153, v109
	v_pk_fma_f32 v[108:109], v[116:117], v[240:241], v[108:109] op_sel_hi:[1,1,0]
	v_and_b32_e32 v152, 0xffff0000, v152
	v_add_f32_e32 v109, 1.0, v123
	v_rcp_f32_e32 v116, v109
	v_fma_f32 v109, -v153, v153, 1.0
	v_sqrt_f32_e32 v117, v109
	v_fmamk_f32 v109, v118, 0xbfb8aa3b, v216
	v_exp_f32_e32 v118, v109
	v_add_f32_e32 v110, 1.0, v110
	v_mul_f32_e32 v116, v116, v117
	v_mov_b32_e32 v117, v186
	v_add_f32_e32 v118, 1.0, v118
	v_rcp_f32_e32 v121, v118
	v_mul_f32_e32 v118, v186, v153
	v_pk_fma_f32 v[116:117], v[116:117], v[152:153], v[118:119] op_sel_hi:[1,1,0]
	v_rcp_f32_e32 v110, v110
	v_mul_f32_e32 v121, v212, v121
	v_exp_f32_e32 v243, v121
	v_fmamk_f32 v104, v104, 0xbfb8aa3b, v210
	v_exp_f32_e32 v104, v104
	v_fmamk_f32 v111, v111, 0xbfb8aa3b, v215
	v_fma_f32 v117, -v243, v243, 1.0
	v_sqrt_f32_e32 v118, v117
	v_fmamk_f32 v117, v119, 0xbfb8aa3b, v217
	v_exp_f32_e32 v121, v117
	v_exp_f32_e32 v123, v111
	v_mul_f32_e32 v118, v110, v118
	v_add_f32_e32 v104, 1.0, v104
	v_add_f32_e32 v110, 1.0, v121
	v_rcp_f32_e32 v121, v110
	v_mov_b32_e32 v119, v188
	v_mul_f32_e32 v110, v188, v243
	v_fmamk_f32 v100, v100, 0xbfb8aa3b, v208
	v_mul_f32_e32 v111, v213, v121
	v_exp_f32_e32 v245, v111
	v_rcp_f32_e32 v121, v104
	v_pk_fma_f32 v[110:111], v[118:119], v[242:243], v[110:111] op_sel_hi:[1,1,0]
	v_exp_f32_e32 v100, v100
	v_add_f32_e32 v111, 1.0, v123
	v_rcp_f32_e32 v118, v111
	v_fma_f32 v111, -v245, v245, 1.0
	v_sqrt_f32_e32 v119, v111
	v_mul_f32_e32 v121, v206, v121
	v_exp_f32_e32 v247, v121
	v_mul_f32_e32 v104, v190, v245
	v_mul_f32_e32 v118, v118, v119
	v_mov_b32_e32 v119, v190
	v_pk_fma_f32 v[118:119], v[118:119], v[244:245], v[104:105] op_sel_hi:[1,1,0]
	v_add_f32_e32 v100, 1.0, v100
	v_fma_f32 v104, -v247, v247, 1.0
	v_fmamk_f32 v105, v105, 0xbfb8aa3b, v211
	v_rcp_f32_e32 v100, v100
	v_sqrt_f32_e32 v104, v104
	v_exp_f32_e32 v121, v105
	v_fmamk_f32 v101, v101, 0xbfb8aa3b, v209
	v_exp_f32_e32 v123, v101
	v_mul_f32_e32 v104, v100, v104
	v_add_f32_e32 v100, 1.0, v121
	v_rcp_f32_e32 v121, v100
	v_lshlrev_b32_e32 v248, 16, v155
	v_and_b32_e32 v250, 0xffff0000, v155
	v_lshlrev_b32_e32 v246, 16, v154
	v_mul_f32_e32 v101, v207, v121
	v_exp_f32_e32 v155, v101
	v_mov_b32_e32 v105, v192
	v_mul_f32_e32 v100, v192, v247
	v_pk_fma_f32 v[100:101], v[104:105], v[246:247], v[100:101] op_sel_hi:[1,1,0]
	v_fmamk_f32 v102, v102, 0xbfb8aa3b, v202
	v_add_f32_e32 v101, 1.0, v123
	v_rcp_f32_e32 v104, v101
	v_fma_f32 v101, -v155, v155, 1.0
	v_sqrt_f32_e32 v105, v101
	v_fmamk_f32 v101, v106, 0xbfb8aa3b, v204
	v_exp_f32_e32 v106, v101
	v_and_b32_e32 v154, 0xffff0000, v154
	v_mul_f32_e32 v104, v104, v105
	v_mov_b32_e32 v105, v194
	v_add_f32_e32 v106, 1.0, v106
	v_rcp_f32_e32 v106, v106
	v_exp_f32_e32 v121, v102
	v_mul_f32_e32 v102, v194, v155
	v_pk_fma_f32 v[104:105], v[104:105], v[154:155], v[102:103] op_sel_hi:[1,1,0]
	v_fmamk_f32 v103, v103, 0xbfb8aa3b, v203
	v_mul_f32_e32 v105, v200, v106
	v_exp_f32_e32 v249, v105
	v_fmamk_f32 v105, v107, 0xbfb8aa3b, v205
	v_exp_f32_e32 v106, v105
	v_add_f32_e32 v102, 1.0, v121
	v_fma_f32 v105, -v249, v249, 1.0
	v_rcp_f32_e32 v102, v102
	v_add_f32_e32 v106, 1.0, v106
	v_sqrt_f32_e32 v107, v105
	v_rcp_f32_e32 v106, v106
	v_mul_f32_e32 v109, v136, v241
	v_mul_f32_e32 v117, v128, v153
	v_mul_f32_e32 v102, v102, v107
	v_exp_f32_e32 v107, v103
	v_mul_f32_e32 v103, v201, v106
	v_exp_f32_e32 v251, v103
	v_mov_b32_e32 v103, v196
	v_add_f32_e32 v106, 1.0, v107
	v_rcp_f32_e32 v107, v106
	v_fma_f32 v106, -v251, v251, 1.0
	v_sqrt_f32_e32 v121, v106
	v_mul_f32_e32 v106, v196, v249
	v_pk_fma_f32 v[102:103], v[102:103], v[248:249], v[106:107] op_sel_hi:[1,1,0]
	v_mul_f32_e32 v152, v198, v251
	v_mul_f32_e32 v106, v107, v121
	v_mov_b32_e32 v107, v198
	v_pk_fma_f32 v[106:107], v[106:107], v[250:251], v[152:153] op_sel_hi:[1,1,0]
	v_mul_f32_e32 v111, v138, v243
	v_mul_f32_e32 v119, v130, v245
	v_mul_f32_e32 v101, v124, v247
	v_mul_f32_e32 v105, v120, v155
	v_mul_f32_e32 v103, v122, v249
	v_mul_f32_e32 v107, v126, v251
	v_fmamk_f32 v96, v96, 0xbfb8aa3b, v222
	v_exp_f32_e32 v96, v96
	v_fmamk_f32 v88, v88, 0xbfb8aa3b, v220
	v_exp_f32_e32 v88, v88
	v_fmamk_f32 v97, v97, 0xbfb8aa3b, v223
	v_add_f32_e32 v96, 1.0, v96
	v_rcp_f32_e32 v96, v96
	v_add_f32_e32 v88, 1.0, v88
	v_rcp_f32_e32 v88, v88
	v_exp_f32_e32 v121, v97
	v_mul_f32_e32 v96, v218, v96
	v_exp_f32_e32 v153, v96
	v_fmamk_f32 v89, v89, 0xbfb8aa3b, v221
	v_exp_f32_e32 v123, v89
	s_waitcnt vmcnt(5)
	v_lshlrev_b32_e32 v154, 16, v149
	v_fma_f32 v96, -v153, v153, 1.0
	v_sqrt_f32_e32 v96, v96
	v_and_b32_e32 v240, 0xffff0000, v149
	v_lshlrev_b32_e32 v152, 16, v148
	v_mov_b32_e32 v97, v108
	v_mul_f32_e32 v96, v88, v96
	v_add_f32_e32 v88, 1.0, v121
	v_rcp_f32_e32 v121, v88
	v_mul_f32_e32 v88, v108, v153
	v_fmamk_f32 v90, v90, 0xbfb8aa3b, v214
	v_exp_f32_e32 v90, v90
	v_mul_f32_e32 v89, v219, v121
	v_exp_f32_e32 v149, v89
	v_pk_fma_f32 v[88:89], v[96:97], v[152:153], v[88:89] op_sel_hi:[1,1,0]
	v_and_b32_e32 v148, 0xffff0000, v148
	v_add_f32_e32 v89, 1.0, v123
	v_rcp_f32_e32 v96, v89
	v_fma_f32 v89, -v149, v149, 1.0
	v_sqrt_f32_e32 v97, v89
	v_fmamk_f32 v89, v98, 0xbfb8aa3b, v216
	v_exp_f32_e32 v98, v89
	v_add_f32_e32 v90, 1.0, v90
	v_mul_f32_e32 v96, v96, v97
	v_mov_b32_e32 v97, v116
	v_add_f32_e32 v98, 1.0, v98
	v_rcp_f32_e32 v121, v98
	v_mul_f32_e32 v98, v116, v149
	v_pk_fma_f32 v[96:97], v[96:97], v[148:149], v[98:99] op_sel_hi:[1,1,0]
	v_rcp_f32_e32 v90, v90
	v_mul_f32_e32 v121, v212, v121
	v_exp_f32_e32 v155, v121
	v_fmamk_f32 v84, v84, 0xbfb8aa3b, v210
	v_exp_f32_e32 v84, v84
	v_fmamk_f32 v91, v91, 0xbfb8aa3b, v215
	v_fma_f32 v97, -v155, v155, 1.0
	v_sqrt_f32_e32 v98, v97
	v_fmamk_f32 v97, v99, 0xbfb8aa3b, v217
	v_exp_f32_e32 v121, v97
	v_exp_f32_e32 v123, v91
	v_mul_f32_e32 v98, v90, v98
	v_add_f32_e32 v84, 1.0, v84
	v_add_f32_e32 v90, 1.0, v121
	v_rcp_f32_e32 v121, v90
	v_mov_b32_e32 v99, v110
	v_mul_f32_e32 v90, v110, v155
	v_fmamk_f32 v80, v80, 0xbfb8aa3b, v208
	v_mul_f32_e32 v91, v213, v121
	v_exp_f32_e32 v241, v91
	v_rcp_f32_e32 v121, v84
	v_pk_fma_f32 v[90:91], v[98:99], v[154:155], v[90:91] op_sel_hi:[1,1,0]
	v_exp_f32_e32 v80, v80
	v_add_f32_e32 v91, 1.0, v123
	v_rcp_f32_e32 v98, v91
	v_fma_f32 v91, -v241, v241, 1.0
	v_sqrt_f32_e32 v99, v91
	v_mul_f32_e32 v121, v206, v121
	v_exp_f32_e32 v243, v121
	v_mul_f32_e32 v84, v118, v241
	v_mul_f32_e32 v98, v98, v99
	v_mov_b32_e32 v99, v118
	v_pk_fma_f32 v[98:99], v[98:99], v[240:241], v[84:85] op_sel_hi:[1,1,0]
	v_add_f32_e32 v80, 1.0, v80
	v_fma_f32 v84, -v243, v243, 1.0
	v_fmamk_f32 v85, v85, 0xbfb8aa3b, v211
	v_rcp_f32_e32 v80, v80
	v_sqrt_f32_e32 v84, v84
	v_exp_f32_e32 v121, v85
	v_fmamk_f32 v81, v81, 0xbfb8aa3b, v209
	v_exp_f32_e32 v123, v81
	v_mul_f32_e32 v84, v80, v84
	v_add_f32_e32 v80, 1.0, v121
	v_rcp_f32_e32 v121, v80
	v_lshlrev_b32_e32 v244, 16, v151
	v_and_b32_e32 v246, 0xffff0000, v151
	v_lshlrev_b32_e32 v242, 16, v150
	v_mul_f32_e32 v81, v207, v121
	v_exp_f32_e32 v151, v81
	v_mov_b32_e32 v85, v100
	v_mul_f32_e32 v80, v100, v243
	v_pk_fma_f32 v[80:81], v[84:85], v[242:243], v[80:81] op_sel_hi:[1,1,0]
	v_fmamk_f32 v82, v82, 0xbfb8aa3b, v202
	v_add_f32_e32 v81, 1.0, v123
	v_rcp_f32_e32 v84, v81
	v_fma_f32 v81, -v151, v151, 1.0
	v_sqrt_f32_e32 v85, v81
	v_fmamk_f32 v81, v86, 0xbfb8aa3b, v204
	v_exp_f32_e32 v86, v81
	v_and_b32_e32 v150, 0xffff0000, v150
	v_mul_f32_e32 v84, v84, v85
	v_mov_b32_e32 v85, v104
	v_add_f32_e32 v86, 1.0, v86
	v_rcp_f32_e32 v86, v86
	v_exp_f32_e32 v121, v82
	v_mul_f32_e32 v82, v104, v151
	v_pk_fma_f32 v[84:85], v[84:85], v[150:151], v[82:83] op_sel_hi:[1,1,0]
	v_fmamk_f32 v83, v83, 0xbfb8aa3b, v203
	v_mul_f32_e32 v85, v200, v86
	v_exp_f32_e32 v245, v85
	v_fmamk_f32 v85, v87, 0xbfb8aa3b, v205
	v_exp_f32_e32 v86, v85
	v_add_f32_e32 v82, 1.0, v121
	v_fma_f32 v85, -v245, v245, 1.0
	v_rcp_f32_e32 v82, v82
	v_add_f32_e32 v86, 1.0, v86
	v_sqrt_f32_e32 v87, v85
	v_rcp_f32_e32 v86, v86
	v_mul_f32_e32 v89, v153, v109
	v_mul_f32_e32 v97, v149, v117
	v_mul_f32_e32 v82, v82, v87
	v_exp_f32_e32 v87, v83
	v_mul_f32_e32 v83, v201, v86
	v_exp_f32_e32 v247, v83
	v_mov_b32_e32 v83, v102
	v_add_f32_e32 v86, 1.0, v87
	v_rcp_f32_e32 v87, v86
	v_fma_f32 v86, -v247, v247, 1.0
	v_sqrt_f32_e32 v121, v86
	v_mul_f32_e32 v86, v102, v245
	v_pk_fma_f32 v[82:83], v[82:83], v[244:245], v[86:87] op_sel_hi:[1,1,0]
	v_mul_f32_e32 v148, v106, v247
	v_mul_f32_e32 v86, v87, v121
	v_mov_b32_e32 v87, v106
	v_pk_fma_f32 v[86:87], v[86:87], v[246:247], v[148:149] op_sel_hi:[1,1,0]
	v_mul_f32_e32 v91, v155, v111
	v_mul_f32_e32 v99, v241, v119
	v_mul_f32_e32 v81, v243, v101
	v_mul_f32_e32 v85, v151, v105
	v_mul_f32_e32 v83, v245, v103
	v_mul_f32_e32 v87, v247, v107
	v_fmamk_f32 v76, v76, 0xbfb8aa3b, v222
	v_exp_f32_e32 v76, v76
	v_fmamk_f32 v72, v72, 0xbfb8aa3b, v220
	v_exp_f32_e32 v72, v72
	v_fmamk_f32 v77, v77, 0xbfb8aa3b, v223
	v_add_f32_e32 v76, 1.0, v76
	v_rcp_f32_e32 v76, v76
	v_add_f32_e32 v72, 1.0, v72
	v_rcp_f32_e32 v72, v72
	v_exp_f32_e32 v121, v77
	v_mul_f32_e32 v76, v218, v76
	v_exp_f32_e32 v149, v76
	v_fmamk_f32 v73, v73, 0xbfb8aa3b, v221
	v_exp_f32_e32 v123, v73
	s_waitcnt vmcnt(4)
	v_lshlrev_b32_e32 v150, 16, v145
	v_fma_f32 v76, -v149, v149, 1.0
	v_sqrt_f32_e32 v76, v76
	v_and_b32_e32 v152, 0xffff0000, v145
	v_lshlrev_b32_e32 v148, 16, v144
	v_mov_b32_e32 v77, v88
	v_mul_f32_e32 v76, v72, v76
	v_add_f32_e32 v72, 1.0, v121
	v_rcp_f32_e32 v121, v72
	v_mul_f32_e32 v72, v88, v149
	v_fmamk_f32 v74, v74, 0xbfb8aa3b, v214
	v_exp_f32_e32 v74, v74
	v_mul_f32_e32 v73, v219, v121
	v_exp_f32_e32 v145, v73
	v_pk_fma_f32 v[72:73], v[76:77], v[148:149], v[72:73] op_sel_hi:[1,1,0]
	v_and_b32_e32 v144, 0xffff0000, v144
	v_add_f32_e32 v73, 1.0, v123
	v_rcp_f32_e32 v76, v73
	v_fma_f32 v73, -v145, v145, 1.0
	v_sqrt_f32_e32 v77, v73
	v_fmamk_f32 v73, v78, 0xbfb8aa3b, v216
	v_exp_f32_e32 v78, v73
	v_add_f32_e32 v74, 1.0, v74
	v_mul_f32_e32 v76, v76, v77
	v_mov_b32_e32 v77, v96
	v_add_f32_e32 v78, 1.0, v78
	v_rcp_f32_e32 v121, v78
	v_mul_f32_e32 v78, v96, v145
	v_pk_fma_f32 v[76:77], v[76:77], v[144:145], v[78:79] op_sel_hi:[1,1,0]
	v_rcp_f32_e32 v74, v74
	v_mul_f32_e32 v121, v212, v121
	v_exp_f32_e32 v151, v121
	v_fmamk_f32 v68, v68, 0xbfb8aa3b, v210
	v_exp_f32_e32 v68, v68
	v_fmamk_f32 v75, v75, 0xbfb8aa3b, v215
	v_fma_f32 v77, -v151, v151, 1.0
	v_sqrt_f32_e32 v78, v77
	v_fmamk_f32 v77, v79, 0xbfb8aa3b, v217
	v_exp_f32_e32 v121, v77
	v_exp_f32_e32 v123, v75
	v_mul_f32_e32 v78, v74, v78
	v_add_f32_e32 v68, 1.0, v68
	v_add_f32_e32 v74, 1.0, v121
	v_rcp_f32_e32 v121, v74
	v_mov_b32_e32 v79, v90
	v_mul_f32_e32 v74, v90, v151
	v_fmamk_f32 v64, v64, 0xbfb8aa3b, v208
	v_mul_f32_e32 v75, v213, v121
	v_exp_f32_e32 v153, v75
	v_rcp_f32_e32 v121, v68
	v_pk_fma_f32 v[74:75], v[78:79], v[150:151], v[74:75] op_sel_hi:[1,1,0]
	v_exp_f32_e32 v64, v64
	v_add_f32_e32 v75, 1.0, v123
	v_rcp_f32_e32 v78, v75
	v_fma_f32 v75, -v153, v153, 1.0
	v_sqrt_f32_e32 v79, v75
	v_mul_f32_e32 v121, v206, v121
	v_exp_f32_e32 v155, v121
	v_mul_f32_e32 v68, v98, v153
	v_mul_f32_e32 v78, v78, v79
	v_mov_b32_e32 v79, v98
	v_pk_fma_f32 v[78:79], v[78:79], v[152:153], v[68:69] op_sel_hi:[1,1,0]
	v_add_f32_e32 v64, 1.0, v64
	v_fma_f32 v68, -v155, v155, 1.0
	v_fmamk_f32 v69, v69, 0xbfb8aa3b, v211
	v_rcp_f32_e32 v64, v64
	v_sqrt_f32_e32 v68, v68
	v_exp_f32_e32 v121, v69
	v_fmamk_f32 v65, v65, 0xbfb8aa3b, v209
	v_exp_f32_e32 v123, v65
	v_mul_f32_e32 v68, v64, v68
	v_add_f32_e32 v64, 1.0, v121
	v_rcp_f32_e32 v121, v64
	v_lshlrev_b32_e32 v240, 16, v147
	v_and_b32_e32 v242, 0xffff0000, v147
	v_lshlrev_b32_e32 v154, 16, v146
	v_mul_f32_e32 v65, v207, v121
	v_exp_f32_e32 v147, v65
	v_mov_b32_e32 v69, v80
	v_mul_f32_e32 v64, v80, v155
	v_pk_fma_f32 v[64:65], v[68:69], v[154:155], v[64:65] op_sel_hi:[1,1,0]
	v_fmamk_f32 v66, v66, 0xbfb8aa3b, v202
	v_add_f32_e32 v65, 1.0, v123
	v_rcp_f32_e32 v68, v65
	v_fma_f32 v65, -v147, v147, 1.0
	v_sqrt_f32_e32 v69, v65
	v_fmamk_f32 v65, v70, 0xbfb8aa3b, v204
	v_exp_f32_e32 v70, v65
	v_and_b32_e32 v146, 0xffff0000, v146
	v_mul_f32_e32 v68, v68, v69
	v_mov_b32_e32 v69, v84
	v_add_f32_e32 v70, 1.0, v70
	v_rcp_f32_e32 v70, v70
	v_exp_f32_e32 v121, v66
	v_mul_f32_e32 v66, v84, v147
	v_pk_fma_f32 v[68:69], v[68:69], v[146:147], v[66:67] op_sel_hi:[1,1,0]
	v_fmamk_f32 v67, v67, 0xbfb8aa3b, v203
	v_mul_f32_e32 v69, v200, v70
	v_exp_f32_e32 v241, v69
	v_fmamk_f32 v69, v71, 0xbfb8aa3b, v205
	v_exp_f32_e32 v70, v69
	v_add_f32_e32 v66, 1.0, v121
	v_fma_f32 v69, -v241, v241, 1.0
	v_rcp_f32_e32 v66, v66
	v_add_f32_e32 v70, 1.0, v70
	v_sqrt_f32_e32 v71, v69
	v_rcp_f32_e32 v70, v70
	v_mul_f32_e32 v73, v149, v89
	v_mul_f32_e32 v77, v145, v97
	v_mul_f32_e32 v66, v66, v71
	v_exp_f32_e32 v71, v67
	v_mul_f32_e32 v67, v201, v70
	v_exp_f32_e32 v243, v67
	v_mov_b32_e32 v67, v82
	v_add_f32_e32 v70, 1.0, v71
	v_rcp_f32_e32 v71, v70
	v_fma_f32 v70, -v243, v243, 1.0
	v_sqrt_f32_e32 v121, v70
	v_mul_f32_e32 v70, v82, v241
	v_pk_fma_f32 v[66:67], v[66:67], v[240:241], v[70:71] op_sel_hi:[1,1,0]
	v_mul_f32_e32 v144, v86, v243
	v_mul_f32_e32 v70, v71, v121
	v_mov_b32_e32 v71, v86
	v_pk_fma_f32 v[70:71], v[70:71], v[242:243], v[144:145] op_sel_hi:[1,1,0]
	v_mul_f32_e32 v75, v151, v91
	v_mul_f32_e32 v79, v153, v99
	v_mul_f32_e32 v65, v155, v81
	v_mul_f32_e32 v69, v147, v85
	v_mul_f32_e32 v67, v241, v83
	v_mul_f32_e32 v71, v243, v87
	v_fmamk_f32 v60, v60, 0xbfb8aa3b, v222
	v_exp_f32_e32 v60, v60
	v_fmamk_f32 v56, v56, 0xbfb8aa3b, v220
	v_exp_f32_e32 v56, v56
	v_fmamk_f32 v61, v61, 0xbfb8aa3b, v223
	v_add_f32_e32 v60, 1.0, v60
	v_rcp_f32_e32 v60, v60
	v_add_f32_e32 v56, 1.0, v56
	v_rcp_f32_e32 v56, v56
	v_exp_f32_e32 v121, v61
	v_mul_f32_e32 v60, v218, v60
	v_exp_f32_e32 v145, v60
	v_fmamk_f32 v57, v57, 0xbfb8aa3b, v221
	v_exp_f32_e32 v123, v57
	s_waitcnt vmcnt(3)
	v_lshlrev_b32_e32 v146, 16, v141
	v_fma_f32 v60, -v145, v145, 1.0
	v_sqrt_f32_e32 v60, v60
	v_and_b32_e32 v148, 0xffff0000, v141
	v_lshlrev_b32_e32 v144, 16, v140
	v_mov_b32_e32 v61, v72
	v_mul_f32_e32 v60, v56, v60
	v_add_f32_e32 v56, 1.0, v121
	v_rcp_f32_e32 v121, v56
	v_mul_f32_e32 v56, v72, v145
	v_fmamk_f32 v58, v58, 0xbfb8aa3b, v214
	v_exp_f32_e32 v58, v58
	v_mul_f32_e32 v57, v219, v121
	v_exp_f32_e32 v141, v57
	v_pk_fma_f32 v[56:57], v[60:61], v[144:145], v[56:57] op_sel_hi:[1,1,0]
	v_and_b32_e32 v140, 0xffff0000, v140
	v_add_f32_e32 v57, 1.0, v123
	v_rcp_f32_e32 v60, v57
	v_fma_f32 v57, -v141, v141, 1.0
	v_sqrt_f32_e32 v61, v57
	v_fmamk_f32 v57, v62, 0xbfb8aa3b, v216
	v_exp_f32_e32 v62, v57
	v_add_f32_e32 v58, 1.0, v58
	v_mul_f32_e32 v60, v60, v61
	v_mov_b32_e32 v61, v76
	v_add_f32_e32 v62, 1.0, v62
	v_rcp_f32_e32 v121, v62
	v_mul_f32_e32 v62, v76, v141
	v_pk_fma_f32 v[60:61], v[60:61], v[140:141], v[62:63] op_sel_hi:[1,1,0]
	v_rcp_f32_e32 v58, v58
	v_mul_f32_e32 v121, v212, v121
	v_exp_f32_e32 v147, v121
	v_fmamk_f32 v52, v52, 0xbfb8aa3b, v210
	v_exp_f32_e32 v52, v52
	v_fmamk_f32 v59, v59, 0xbfb8aa3b, v215
	v_fma_f32 v61, -v147, v147, 1.0
	v_sqrt_f32_e32 v62, v61
	v_fmamk_f32 v61, v63, 0xbfb8aa3b, v217
	v_exp_f32_e32 v121, v61
	v_exp_f32_e32 v123, v59
	v_mul_f32_e32 v62, v58, v62
	v_add_f32_e32 v52, 1.0, v52
	v_add_f32_e32 v58, 1.0, v121
	v_rcp_f32_e32 v121, v58
	v_mov_b32_e32 v63, v74
	v_mul_f32_e32 v58, v74, v147
	v_fmamk_f32 v48, v48, 0xbfb8aa3b, v208
	v_mul_f32_e32 v59, v213, v121
	v_exp_f32_e32 v149, v59
	v_rcp_f32_e32 v121, v52
	v_pk_fma_f32 v[58:59], v[62:63], v[146:147], v[58:59] op_sel_hi:[1,1,0]
	v_exp_f32_e32 v48, v48
	v_add_f32_e32 v59, 1.0, v123
	v_rcp_f32_e32 v62, v59
	v_fma_f32 v59, -v149, v149, 1.0
	v_sqrt_f32_e32 v63, v59
	v_mul_f32_e32 v121, v206, v121
	v_exp_f32_e32 v151, v121
	v_mul_f32_e32 v52, v78, v149
	v_mul_f32_e32 v62, v62, v63
	v_mov_b32_e32 v63, v78
	v_pk_fma_f32 v[62:63], v[62:63], v[148:149], v[52:53] op_sel_hi:[1,1,0]
	v_add_f32_e32 v48, 1.0, v48
	v_fma_f32 v52, -v151, v151, 1.0
	v_fmamk_f32 v53, v53, 0xbfb8aa3b, v211
	v_rcp_f32_e32 v48, v48
	v_sqrt_f32_e32 v52, v52
	v_exp_f32_e32 v121, v53
	v_fmamk_f32 v49, v49, 0xbfb8aa3b, v209
	v_exp_f32_e32 v123, v49
	v_mul_f32_e32 v52, v48, v52
	v_add_f32_e32 v48, 1.0, v121
	v_rcp_f32_e32 v121, v48
	v_lshlrev_b32_e32 v152, 16, v143
	v_and_b32_e32 v154, 0xffff0000, v143
	v_lshlrev_b32_e32 v150, 16, v142
	v_mul_f32_e32 v49, v207, v121
	v_exp_f32_e32 v143, v49
	v_mov_b32_e32 v53, v64
	v_mul_f32_e32 v48, v64, v151
	v_pk_fma_f32 v[48:49], v[52:53], v[150:151], v[48:49] op_sel_hi:[1,1,0]
	v_fmamk_f32 v50, v50, 0xbfb8aa3b, v202
	v_add_f32_e32 v49, 1.0, v123
	v_rcp_f32_e32 v52, v49
	v_fma_f32 v49, -v143, v143, 1.0
	v_sqrt_f32_e32 v53, v49
	v_fmamk_f32 v49, v54, 0xbfb8aa3b, v204
	v_exp_f32_e32 v54, v49
	v_and_b32_e32 v142, 0xffff0000, v142
	v_mul_f32_e32 v52, v52, v53
	v_mov_b32_e32 v53, v68
	v_add_f32_e32 v54, 1.0, v54
	v_rcp_f32_e32 v54, v54
	v_exp_f32_e32 v121, v50
	v_mul_f32_e32 v50, v68, v143
	v_pk_fma_f32 v[52:53], v[52:53], v[142:143], v[50:51] op_sel_hi:[1,1,0]
	v_fmamk_f32 v51, v51, 0xbfb8aa3b, v203
	v_mul_f32_e32 v53, v200, v54
	v_exp_f32_e32 v153, v53
	v_fmamk_f32 v53, v55, 0xbfb8aa3b, v205
	v_exp_f32_e32 v54, v53
	v_add_f32_e32 v50, 1.0, v121
	v_fma_f32 v53, -v153, v153, 1.0
	v_rcp_f32_e32 v50, v50
	v_add_f32_e32 v54, 1.0, v54
	v_sqrt_f32_e32 v55, v53
	v_rcp_f32_e32 v54, v54
	v_mul_f32_e32 v57, v145, v73
	v_mul_f32_e32 v61, v141, v77
	v_mul_f32_e32 v50, v50, v55
	v_exp_f32_e32 v55, v51
	v_mul_f32_e32 v51, v201, v54
	v_exp_f32_e32 v155, v51
	v_mov_b32_e32 v51, v66
	v_add_f32_e32 v54, 1.0, v55
	v_rcp_f32_e32 v55, v54
	v_fma_f32 v54, -v155, v155, 1.0
	v_sqrt_f32_e32 v121, v54
	v_mul_f32_e32 v54, v66, v153
	v_pk_fma_f32 v[50:51], v[50:51], v[152:153], v[54:55] op_sel_hi:[1,1,0]
	v_mul_f32_e32 v140, v70, v155
	v_mul_f32_e32 v54, v55, v121
	v_mov_b32_e32 v55, v70
	v_pk_fma_f32 v[54:55], v[54:55], v[154:155], v[140:141] op_sel_hi:[1,1,0]
	v_mul_f32_e32 v59, v147, v75
	v_mul_f32_e32 v63, v149, v79
	v_mul_f32_e32 v49, v151, v65
	v_mul_f32_e32 v53, v143, v69
	v_mul_f32_e32 v51, v153, v67
	v_mul_f32_e32 v55, v155, v71
	v_fmamk_f32 v44, v44, 0xbfb8aa3b, v222
	v_exp_f32_e32 v44, v44
	v_fmamk_f32 v40, v40, 0xbfb8aa3b, v220
	v_exp_f32_e32 v40, v40
	v_fmamk_f32 v45, v45, 0xbfb8aa3b, v223
	v_add_f32_e32 v44, 1.0, v44
	v_rcp_f32_e32 v44, v44
	v_add_f32_e32 v40, 1.0, v40
	v_rcp_f32_e32 v40, v40
	v_exp_f32_e32 v121, v45
	v_mul_f32_e32 v44, v218, v44
	v_exp_f32_e32 v141, v44
	v_fmamk_f32 v41, v41, 0xbfb8aa3b, v221
	v_exp_f32_e32 v123, v41
	s_waitcnt vmcnt(2)
	v_lshlrev_b32_e32 v142, 16, v133
	v_fma_f32 v44, -v141, v141, 1.0
	v_sqrt_f32_e32 v44, v44
	v_and_b32_e32 v144, 0xffff0000, v133
	v_lshlrev_b32_e32 v140, 16, v132
	v_mov_b32_e32 v45, v56
	v_mul_f32_e32 v44, v40, v44
	v_add_f32_e32 v40, 1.0, v121
	v_rcp_f32_e32 v121, v40
	v_mul_f32_e32 v40, v56, v141
	v_fmamk_f32 v42, v42, 0xbfb8aa3b, v214
	v_exp_f32_e32 v42, v42
	v_mul_f32_e32 v41, v219, v121
	v_exp_f32_e32 v133, v41
	v_pk_fma_f32 v[40:41], v[44:45], v[140:141], v[40:41] op_sel_hi:[1,1,0]
	v_and_b32_e32 v132, 0xffff0000, v132
	v_add_f32_e32 v41, 1.0, v123
	v_rcp_f32_e32 v44, v41
	v_fma_f32 v41, -v133, v133, 1.0
	v_sqrt_f32_e32 v45, v41
	v_fmamk_f32 v41, v46, 0xbfb8aa3b, v216
	v_exp_f32_e32 v46, v41
	v_add_f32_e32 v42, 1.0, v42
	v_mul_f32_e32 v44, v44, v45
	v_mov_b32_e32 v45, v60
	v_add_f32_e32 v46, 1.0, v46
	v_rcp_f32_e32 v121, v46
	v_mul_f32_e32 v46, v60, v133
	v_pk_fma_f32 v[44:45], v[44:45], v[132:133], v[46:47] op_sel_hi:[1,1,0]
	v_rcp_f32_e32 v42, v42
	v_mul_f32_e32 v121, v212, v121
	v_exp_f32_e32 v143, v121
	v_fmamk_f32 v36, v36, 0xbfb8aa3b, v210
	v_exp_f32_e32 v36, v36
	v_fmamk_f32 v43, v43, 0xbfb8aa3b, v215
	v_fma_f32 v45, -v143, v143, 1.0
	v_sqrt_f32_e32 v46, v45
	v_fmamk_f32 v45, v47, 0xbfb8aa3b, v217
	v_exp_f32_e32 v121, v45
	v_exp_f32_e32 v123, v43
	v_mul_f32_e32 v46, v42, v46
	v_add_f32_e32 v36, 1.0, v36
	v_add_f32_e32 v42, 1.0, v121
	v_rcp_f32_e32 v121, v42
	v_mov_b32_e32 v47, v58
	v_mul_f32_e32 v42, v58, v143
	v_fmamk_f32 v32, v32, 0xbfb8aa3b, v208
	v_mul_f32_e32 v43, v213, v121
	v_exp_f32_e32 v145, v43
	v_rcp_f32_e32 v121, v36
	v_pk_fma_f32 v[42:43], v[46:47], v[142:143], v[42:43] op_sel_hi:[1,1,0]
	v_exp_f32_e32 v32, v32
	v_add_f32_e32 v43, 1.0, v123
	v_rcp_f32_e32 v46, v43
	v_fma_f32 v43, -v145, v145, 1.0
	v_sqrt_f32_e32 v47, v43
	v_mul_f32_e32 v121, v206, v121
	v_exp_f32_e32 v147, v121
	v_mul_f32_e32 v36, v62, v145
	v_mul_f32_e32 v46, v46, v47
	v_mov_b32_e32 v47, v62
	v_pk_fma_f32 v[46:47], v[46:47], v[144:145], v[36:37] op_sel_hi:[1,1,0]
	v_add_f32_e32 v32, 1.0, v32
	v_fma_f32 v36, -v147, v147, 1.0
	v_fmamk_f32 v37, v37, 0xbfb8aa3b, v211
	v_rcp_f32_e32 v32, v32
	v_sqrt_f32_e32 v36, v36
	v_exp_f32_e32 v121, v37
	v_fmamk_f32 v33, v33, 0xbfb8aa3b, v209
	v_exp_f32_e32 v123, v33
	v_mul_f32_e32 v36, v32, v36
	v_add_f32_e32 v32, 1.0, v121
	v_rcp_f32_e32 v121, v32
	v_lshlrev_b32_e32 v148, 16, v135
	v_and_b32_e32 v150, 0xffff0000, v135
	v_lshlrev_b32_e32 v146, 16, v134
	v_mul_f32_e32 v33, v207, v121
	v_exp_f32_e32 v135, v33
	v_mov_b32_e32 v37, v48
	v_mul_f32_e32 v32, v48, v147
	v_pk_fma_f32 v[32:33], v[36:37], v[146:147], v[32:33] op_sel_hi:[1,1,0]
	v_fmamk_f32 v34, v34, 0xbfb8aa3b, v202
	v_add_f32_e32 v33, 1.0, v123
	v_rcp_f32_e32 v36, v33
	v_fma_f32 v33, -v135, v135, 1.0
	v_sqrt_f32_e32 v37, v33
	v_fmamk_f32 v33, v38, 0xbfb8aa3b, v204
	v_exp_f32_e32 v38, v33
	v_and_b32_e32 v134, 0xffff0000, v134
	v_mul_f32_e32 v36, v36, v37
	v_mov_b32_e32 v37, v52
	v_add_f32_e32 v38, 1.0, v38
	v_rcp_f32_e32 v38, v38
	v_exp_f32_e32 v121, v34
	v_mul_f32_e32 v34, v52, v135
	v_pk_fma_f32 v[36:37], v[36:37], v[134:135], v[34:35] op_sel_hi:[1,1,0]
	v_fmamk_f32 v35, v35, 0xbfb8aa3b, v203
	v_mul_f32_e32 v37, v200, v38
	v_exp_f32_e32 v149, v37
	v_fmamk_f32 v37, v39, 0xbfb8aa3b, v205
	v_exp_f32_e32 v38, v37
	v_add_f32_e32 v34, 1.0, v121
	v_fma_f32 v37, -v149, v149, 1.0
	v_rcp_f32_e32 v34, v34
	v_add_f32_e32 v38, 1.0, v38
	v_sqrt_f32_e32 v39, v37
	v_rcp_f32_e32 v38, v38
	v_mul_f32_e32 v41, v141, v57
	v_mul_f32_e32 v45, v133, v61
	v_mul_f32_e32 v34, v34, v39
	v_exp_f32_e32 v39, v35
	v_mul_f32_e32 v35, v201, v38
	v_exp_f32_e32 v151, v35
	v_mov_b32_e32 v35, v50
	v_add_f32_e32 v38, 1.0, v39
	v_rcp_f32_e32 v39, v38
	v_fma_f32 v38, -v151, v151, 1.0
	v_sqrt_f32_e32 v121, v38
	v_mul_f32_e32 v38, v50, v149
	v_pk_fma_f32 v[34:35], v[34:35], v[148:149], v[38:39] op_sel_hi:[1,1,0]
	v_mul_f32_e32 v132, v54, v151
	v_mul_f32_e32 v38, v39, v121
	v_mov_b32_e32 v39, v54
	v_pk_fma_f32 v[38:39], v[38:39], v[150:151], v[132:133] op_sel_hi:[1,1,0]
	v_mul_f32_e32 v43, v143, v59
	v_mul_f32_e32 v47, v145, v63
	v_mul_f32_e32 v33, v147, v49
	v_mul_f32_e32 v37, v135, v53
	v_mul_f32_e32 v35, v149, v51
	v_mul_f32_e32 v39, v151, v55
	v_fmamk_f32 v28, v28, 0xbfb8aa3b, v222
	s_waitcnt vmcnt(1)
	v_lshlrev_b32_e32 v132, 16, v112
	v_and_b32_e32 v134, 0xffff0000, v112
	v_exp_f32_e32 v112, v28
	v_fmamk_f32 v29, v29, 0xbfb8aa3b, v223
	v_exp_f32_e32 v29, v29
	v_fmamk_f32 v24, v24, 0xbfb8aa3b, v220
	v_add_f32_e32 v112, 1.0, v112
	v_rcp_f32_e32 v112, v112
	v_add_f32_e32 v29, 1.0, v29
	v_rcp_f32_e32 v29, v29
	v_lshlrev_b32_e32 v28, 16, v113
	v_and_b32_e32 v140, 0xffff0000, v113
	v_exp_f32_e32 v113, v24
	v_mul_f32_e32 v24, v218, v112
	v_exp_f32_e32 v133, v24
	v_fmamk_f32 v25, v25, 0xbfb8aa3b, v221
	v_mul_f32_e32 v29, v219, v29
	v_exp_f32_e32 v25, v25
	v_exp_f32_e32 v135, v29
	v_add_f32_e32 v112, 1.0, v113
	v_fma_f32 v113, -v133, v133, 1.0
	v_rcp_f32_e32 v112, v112
	v_sqrt_f32_e32 v113, v113
	v_add_f32_e32 v25, 1.0, v25
	v_fma_f32 v29, -v135, v135, 1.0
	v_fmamk_f32 v30, v30, 0xbfb8aa3b, v216
	v_rcp_f32_e32 v25, v25
	v_sqrt_f32_e32 v29, v29
	v_exp_f32_e32 v30, v30
	v_lshlrev_b32_e32 v142, 16, v114
	v_and_b32_e32 v144, 0xffff0000, v114
	v_mul_f32_e32 v112, v112, v113
	v_mov_b32_e32 v113, v40
	v_mul_f32_e32 v114, v40, v133
	v_pk_fma_f32 v[112:113], v[112:113], v[132:133], v[114:115] op_sel_hi:[1,1,0]
	v_mul_f32_e32 v114, v25, v29
	v_add_f32_e32 v25, 1.0, v30
	v_rcp_f32_e32 v25, v25
	v_fmamk_f32 v26, v26, 0xbfb8aa3b, v214
	v_exp_f32_e32 v26, v26
	v_lshlrev_b32_e32 v24, 16, v115
	v_mul_f32_e32 v25, v212, v25
	v_exp_f32_e32 v29, v25
	v_and_b32_e32 v148, 0xffff0000, v115
	v_mov_b32_e32 v115, v44
	v_mul_f32_e32 v30, v44, v135
	v_pk_fma_f32 v[114:115], v[114:115], v[134:135], v[30:31] op_sel_hi:[1,1,0]
	v_add_f32_e32 v25, 1.0, v26
	v_fma_f32 v26, -v29, v29, 1.0
	v_fmamk_f32 v30, v31, 0xbfb8aa3b, v217
	v_rcp_f32_e32 v25, v25
	v_sqrt_f32_e32 v26, v26
	v_exp_f32_e32 v121, v30
	v_fmamk_f32 v27, v27, 0xbfb8aa3b, v215
	v_exp_f32_e32 v27, v27
	v_mul_f32_e32 v30, v25, v26
	v_add_f32_e32 v25, 1.0, v121
	v_rcp_f32_e32 v25, v25
	v_mov_b32_e32 v31, v42
	v_mul_f32_e32 v26, v42, v29
	v_fmamk_f32 v20, v20, 0xbfb8aa3b, v210
	v_mul_f32_e32 v25, v213, v25
	v_exp_f32_e32 v141, v25
	v_mul_f32_e32 v113, v133, v41
	v_pk_fma_f32 v[132:133], v[30:31], v[28:29], v[26:27] op_sel_hi:[1,1,0]
	v_add_f32_e32 v25, 1.0, v27
	v_fma_f32 v26, -v141, v141, 1.0
	v_exp_f32_e32 v20, v20
	v_rcp_f32_e32 v25, v25
	v_sqrt_f32_e32 v26, v26
	v_fmamk_f32 v16, v16, 0xbfb8aa3b, v208
	v_add_f32_e32 v20, 1.0, v20
	v_exp_f32_e32 v16, v16
	v_mul_f32_e32 v26, v25, v26
	v_rcp_f32_e32 v25, v20
	v_mov_b32_e32 v27, v46
	v_mul_f32_e32 v20, v46, v141
	v_mul_f32_e32 v115, v135, v45
	v_mul_f32_e32 v25, v206, v25
	v_exp_f32_e32 v143, v25
	v_pk_fma_f32 v[134:135], v[26:27], v[140:141], v[20:21] op_sel_hi:[1,1,0]
	v_add_f32_e32 v16, 1.0, v16
	v_fmamk_f32 v21, v21, 0xbfb8aa3b, v211
	v_fma_f32 v20, -v143, v143, 1.0
	v_rcp_f32_e32 v16, v16
	v_sqrt_f32_e32 v20, v20
	v_exp_f32_e32 v25, v21
	v_fmamk_f32 v17, v17, 0xbfb8aa3b, v209
	v_exp_f32_e32 v17, v17
	v_mul_f32_e32 v20, v16, v20
	v_add_f32_e32 v16, 1.0, v25
	v_rcp_f32_e32 v25, v16
	v_mov_b32_e32 v21, v32
	v_mul_f32_e32 v16, v32, v143
	v_mul_f32_e32 v123, v141, v47
	v_mul_f32_e32 v25, v207, v25
	v_exp_f32_e32 v145, v25
	v_pk_fma_f32 v[140:141], v[20:21], v[142:143], v[16:17] op_sel_hi:[1,1,0]
	v_fmamk_f32 v20, v22, 0xbfb8aa3b, v204
	v_exp_f32_e32 v20, v20
	v_add_f32_e32 v16, 1.0, v17
	v_fma_f32 v17, -v145, v145, 1.0
	v_rcp_f32_e32 v16, v16
	v_sqrt_f32_e32 v17, v17
	v_add_f32_e32 v20, 1.0, v20
	v_rcp_f32_e32 v20, v20
	v_fmamk_f32 v18, v18, 0xbfb8aa3b, v202
	v_mul_f32_e32 v16, v16, v17
	v_mov_b32_e32 v17, v36
	v_exp_f32_e32 v21, v18
	v_mul_f32_e32 v18, v36, v145
	v_mul_f32_e32 v125, v143, v33
	v_pk_fma_f32 v[142:143], v[16:17], v[144:145], v[18:19] op_sel_hi:[1,1,0]
	v_mul_f32_e32 v17, v200, v20
	v_exp_f32_e32 v25, v17
	v_fmamk_f32 v17, v23, 0xbfb8aa3b, v205
	v_exp_f32_e32 v17, v17
	v_add_f32_e32 v16, 1.0, v21
	v_fma_f32 v18, -v25, v25, 1.0
	v_rcp_f32_e32 v16, v16
	v_sqrt_f32_e32 v18, v18
	v_add_f32_e32 v17, 1.0, v17
	v_rcp_f32_e32 v17, v17
	v_mul_f32_e32 v127, v145, v37
	v_mul_f32_e32 v16, v16, v18
	v_fmamk_f32 v18, v19, 0xbfb8aa3b, v203
	v_exp_f32_e32 v18, v18
	v_mul_f32_e32 v17, v201, v17
	v_exp_f32_e32 v149, v17
	v_mov_b32_e32 v17, v34
	v_add_f32_e32 v18, 1.0, v18
	v_rcp_f32_e32 v19, v18
	v_fma_f32 v18, -v149, v149, 1.0
	v_sqrt_f32_e32 v20, v18
	v_mul_f32_e32 v18, v34, v25
	v_pk_fma_f32 v[144:145], v[16:17], v[24:25], v[18:19] op_sel_hi:[1,1,0]
	v_mov_b32_e32 v17, v38
	v_mul_f32_e32 v16, v19, v20
	v_mul_f32_e32 v18, v38, v149
	v_mul_f32_e32 v121, v29, v43
	v_mul_f32_e32 v129, v25, v35
	v_pk_fma_f32 v[146:147], v[16:17], v[148:149], v[18:19] op_sel_hi:[1,1,0]
	v_mul_f32_e32 v131, v149, v39
	v_fmamk_f32 v12, v12, 0xbfb8aa3b, v222
	v_exp_f32_e32 v17, v12
	v_fmamk_f32 v8, v8, 0xbfb8aa3b, v220
	v_fmac_f32_e32 v223, 0xbfb8aa3b, v13
	v_exp_f32_e32 v19, v8
	v_add_f32_e32 v17, 1.0, v17
	v_rcp_f32_e32 v17, v17
	v_exp_f32_e32 v13, v223
	v_add_f32_e32 v19, 1.0, v19
	v_rcp_f32_e32 v19, v19
	v_mul_f32_e32 v8, v218, v17
	v_exp_f32_e32 v17, v8
	v_add_f32_e32 v13, 1.0, v13
	v_rcp_f32_e32 v13, v13
	v_fmac_f32_e32 v221, 0xbfb8aa3b, v9
	v_fma_f32 v21, -v17, v17, 1.0
	v_sqrt_f32_e32 v21, v21
	v_mul_f32_e32 v13, v219, v13
	v_exp_f32_e32 v9, v221
	v_fmamk_f32 v14, v14, 0xbfb8aa3b, v216
	v_mul_f32_e32 v28, v19, v21
	v_exp_f32_e32 v19, v13
	v_add_f32_e32 v9, 1.0, v9
	v_rcp_f32_e32 v9, v9
	v_exp_f32_e32 v14, v14
	v_fma_f32 v13, -v19, v19, 1.0
	v_sqrt_f32_e32 v13, v13
	s_waitcnt vmcnt(0)
	v_lshlrev_b32_e32 v16, 16, v92
	v_mov_b32_e32 v29, v112
	v_pk_mul_f32 v[28:29], v[28:29], v[16:17]
	v_mul_f32_e32 v16, v9, v13
	v_add_f32_e32 v9, 1.0, v14
	v_rcp_f32_e32 v9, v9
	v_fmamk_f32 v10, v10, 0xbfb8aa3b, v214
	v_exp_f32_e32 v10, v10
	v_and_b32_e32 v18, 0xffff0000, v92
	v_mul_f32_e32 v9, v212, v9
	v_exp_f32_e32 v13, v9
	v_mul_f32_e32 v135, v17, v113
	v_mov_b32_e32 v17, v114
	v_pk_mul_f32 v[16:17], v[16:17], v[18:19]
	v_add_f32_e32 v9, 1.0, v10
	v_fma_f32 v10, -v13, v13, 1.0
	v_fmac_f32_e32 v217, 0xbfb8aa3b, v15
	v_add_f32_e32 v137, v16, v17
	v_rcp_f32_e32 v9, v9
	v_sqrt_f32_e32 v10, v10
	v_exp_f32_e32 v16, v217
	v_fmamk_f32 v4, v4, 0xbfb8aa3b, v210
	v_exp_f32_e32 v4, v4
	v_mul_f32_e32 v14, v9, v10
	v_add_f32_e32 v9, 1.0, v16
	v_rcp_f32_e32 v9, v9
	v_add_f32_e32 v4, 1.0, v4
	v_fmac_f32_e32 v215, 0xbfb8aa3b, v11
	v_rcp_f32_e32 v4, v4
	v_mul_f32_e32 v9, v213, v9
	v_exp_f32_e32 v10, v215
	v_exp_f32_e32 v21, v9
	v_fmamk_f32 v0, v0, 0xbfb8aa3b, v208
	v_mul_f32_e32 v4, v206, v4
	v_add_f32_e32 v9, 1.0, v10
	v_fma_f32 v10, -v21, v21, 1.0
	v_exp_f32_e32 v0, v0
	v_exp_f32_e32 v23, v4
	v_rcp_f32_e32 v9, v9
	v_sqrt_f32_e32 v10, v10
	v_add_f32_e32 v0, 1.0, v0
	v_fma_f32 v4, -v23, v23, 1.0
	v_fmac_f32_e32 v211, 0xbfb8aa3b, v5
	v_mul_f32_e32 v10, v9, v10
	v_rcp_f32_e32 v0, v0
	v_sqrt_f32_e32 v4, v4
	v_exp_f32_e32 v9, v211
	v_lshlrev_b32_e32 v22, 16, v94
	v_mov_b32_e32 v5, v140
	v_mul_f32_e32 v4, v0, v4
	v_add_f32_e32 v0, 1.0, v9
	v_rcp_f32_e32 v0, v0
	v_fmac_f32_e32 v209, 0xbfb8aa3b, v1
	v_pk_mul_f32 v[4:5], v[4:5], v[22:23]
	v_exp_f32_e32 v1, v209
	v_mul_f32_e32 v0, v207, v0
	v_exp_f32_e32 v25, v0
	v_add_f32_e32 v147, v4, v5
	v_fmamk_f32 v4, v6, 0xbfb8aa3b, v204
	v_exp_f32_e32 v4, v4
	v_add_f32_e32 v0, 1.0, v1
	v_fma_f32 v1, -v25, v25, 1.0
	v_rcp_f32_e32 v0, v0
	v_sqrt_f32_e32 v1, v1
	v_add_f32_e32 v4, 1.0, v4
	v_rcp_f32_e32 v4, v4
	v_and_b32_e32 v24, 0xffff0000, v94
	v_mul_f32_e32 v0, v0, v1
	v_mov_b32_e32 v1, v142
	v_pk_mul_f32 v[0:1], v[0:1], v[24:25]
	v_fmac_f32_e32 v205, 0xbfb8aa3b, v7
	v_add_f32_e32 v187, v0, v1
	v_mul_f32_e32 v1, v200, v4
	v_fmamk_f32 v2, v2, 0xbfb8aa3b, v202
	v_exp_f32_e32 v9, v1
	v_exp_f32_e32 v1, v205
	v_exp_f32_e32 v2, v2
	v_fmac_f32_e32 v203, 0xbfb8aa3b, v3
	v_lshlrev_b32_e32 v8, 16, v95
	v_add_f32_e32 v1, 1.0, v1
	v_add_f32_e32 v0, 1.0, v2
	v_fma_f32 v2, -v9, v9, 1.0
	v_rcp_f32_e32 v1, v1
	v_rcp_f32_e32 v0, v0
	v_sqrt_f32_e32 v2, v2
	v_lshlrev_b32_e32 v12, 16, v93
	v_mul_f32_e32 v1, v201, v1
	v_exp_f32_e32 v27, v1
	v_mul_f32_e32 v0, v0, v2
	v_exp_f32_e32 v2, v203
	v_mov_b32_e32 v1, v144
	v_fma_f32 v3, -v27, v27, 1.0
	v_sqrt_f32_e32 v3, v3
	v_add_f32_e32 v2, 1.0, v2
	v_rcp_f32_e32 v2, v2
	v_pk_mul_f32 v[0:1], v[0:1], v[8:9]
	v_and_b32_e32 v20, 0xffff0000, v93
	v_and_b32_e32 v26, 0xffff0000, v95
	v_mov_b32_e32 v15, v132
	v_mov_b32_e32 v11, v134
	v_add_f32_e32 v193, v0, v1
	v_mul_f32_e32 v0, v2, v3
	v_mov_b32_e32 v1, v146
	v_pk_mul_f32 v[14:15], v[14:15], v[12:13]
	v_pk_mul_f32 v[10:11], v[10:11], v[20:21]
	v_pk_mul_f32 v[0:1], v[0:1], v[26:27]
	v_add_f32_e32 v133, v28, v29
	v_mul_f32_e32 v141, v19, v115
	v_add_f32_e32 v139, v14, v15
	v_mul_f32_e32 v143, v13, v121
	v_add_f32_e32 v145, v10, v11
	v_mul_f32_e32 v185, v21, v123
	v_mul_f32_e32 v189, v23, v125
	v_mul_f32_e32 v191, v25, v127
	v_mul_f32_e32 v197, v9, v129
	v_add_f32_e32 v195, v0, v1
	v_mul_f32_e32 v199, v27, v131
	v_mov_b32_e32 v0, v135
	v_mov_b32_e32 v17, v133
	v_mov_b32_e32 v2, v141
	v_mov_b32_e32 v19, v137
	v_mov_b32_e32 v4, v143
	v_mov_b32_e32 v21, v139
	v_mov_b32_e32 v6, v185
	v_mov_b32_e32 v23, v145
	v_mov_b32_e32 v8, v189
	v_mov_b32_e32 v25, v147
	v_mov_b32_e32 v10, v191
	v_mov_b32_e32 v27, v187
	v_mov_b32_e32 v12, v197
	v_mov_b32_e32 v31, v193
	v_mov_b32_e32 v14, v199
	v_mov_b32_e32 v205, v195
	v_fmac_f32_dpp v17, v17, v0 row_shr:1 row_mask:0xf bank_mask:0xf
	v_fmac_f32_dpp v19, v19, v2 row_shr:1 row_mask:0xf bank_mask:0xf
	v_fmac_f32_dpp v21, v21, v4 row_shr:1 row_mask:0xf bank_mask:0xf
	v_fmac_f32_dpp v23, v23, v6 row_shr:1 row_mask:0xf bank_mask:0xf
	v_fmac_f32_dpp v25, v25, v8 row_shr:1 row_mask:0xf bank_mask:0xf
	v_fmac_f32_dpp v27, v27, v10 row_shr:1 row_mask:0xf bank_mask:0xf
	v_fmac_f32_dpp v31, v31, v12 row_shr:1 row_mask:0xf bank_mask:0xf
	v_fmac_f32_dpp v205, v205, v14 row_shr:1 row_mask:0xf bank_mask:0xf
	v_mul_f32_dpp v0, v0, v0 row_shr:1 row_mask:0xf bank_mask:0xf
	v_mul_f32_dpp v2, v2, v2 row_shr:1 row_mask:0xf bank_mask:0xf
	v_mul_f32_dpp v4, v4, v4 row_shr:1 row_mask:0xf bank_mask:0xf
	v_mul_f32_dpp v6, v6, v6 row_shr:1 row_mask:0xf bank_mask:0xf
	v_mul_f32_dpp v8, v8, v8 row_shr:1 row_mask:0xf bank_mask:0xf
	v_mul_f32_dpp v10, v10, v10 row_shr:1 row_mask:0xf bank_mask:0xf
	v_mul_f32_dpp v12, v12, v12 row_shr:1 row_mask:0xf bank_mask:0xf
	v_mul_f32_dpp v14, v14, v14 row_shr:1 row_mask:0xf bank_mask:0xf
	v_fmac_f32_dpp v17, v17, v0 row_shr:2 row_mask:0xf bank_mask:0xf
	v_fmac_f32_dpp v19, v19, v2 row_shr:2 row_mask:0xf bank_mask:0xf
	v_fmac_f32_dpp v21, v21, v4 row_shr:2 row_mask:0xf bank_mask:0xf
	v_fmac_f32_dpp v23, v23, v6 row_shr:2 row_mask:0xf bank_mask:0xf
	v_fmac_f32_dpp v25, v25, v8 row_shr:2 row_mask:0xf bank_mask:0xf
	v_fmac_f32_dpp v27, v27, v10 row_shr:2 row_mask:0xf bank_mask:0xf
	v_fmac_f32_dpp v31, v31, v12 row_shr:2 row_mask:0xf bank_mask:0xf
	v_fmac_f32_dpp v205, v205, v14 row_shr:2 row_mask:0xf bank_mask:0xf
	v_mul_f32_dpp v0, v0, v0 row_shr:2 row_mask:0xf bank_mask:0xf
	v_mul_f32_dpp v2, v2, v2 row_shr:2 row_mask:0xf bank_mask:0xf
	v_mul_f32_dpp v4, v4, v4 row_shr:2 row_mask:0xf bank_mask:0xf
	v_mul_f32_dpp v6, v6, v6 row_shr:2 row_mask:0xf bank_mask:0xf
	v_mul_f32_dpp v8, v8, v8 row_shr:2 row_mask:0xf bank_mask:0xf
	v_mul_f32_dpp v10, v10, v10 row_shr:2 row_mask:0xf bank_mask:0xf
	v_mul_f32_dpp v12, v12, v12 row_shr:2 row_mask:0xf bank_mask:0xf
	v_mul_f32_dpp v14, v14, v14 row_shr:2 row_mask:0xf bank_mask:0xf
	v_fmac_f32_dpp v17, v17, v0 row_shr:4 row_mask:0xf bank_mask:0xf
	v_fmac_f32_dpp v19, v19, v2 row_shr:4 row_mask:0xf bank_mask:0xf
	v_fmac_f32_dpp v21, v21, v4 row_shr:4 row_mask:0xf bank_mask:0xf
	v_fmac_f32_dpp v23, v23, v6 row_shr:4 row_mask:0xf bank_mask:0xf
	v_fmac_f32_dpp v25, v25, v8 row_shr:4 row_mask:0xf bank_mask:0xf
	v_fmac_f32_dpp v27, v27, v10 row_shr:4 row_mask:0xf bank_mask:0xf
	v_fmac_f32_dpp v31, v31, v12 row_shr:4 row_mask:0xf bank_mask:0xf
	v_fmac_f32_dpp v205, v205, v14 row_shr:4 row_mask:0xf bank_mask:0xf
	v_mul_f32_dpp v0, v0, v0 row_shr:4 row_mask:0xf bank_mask:0xf
	v_mul_f32_dpp v2, v2, v2 row_shr:4 row_mask:0xf bank_mask:0xf
	v_mul_f32_dpp v4, v4, v4 row_shr:4 row_mask:0xf bank_mask:0xf
	v_mul_f32_dpp v6, v6, v6 row_shr:4 row_mask:0xf bank_mask:0xf
	v_mul_f32_dpp v8, v8, v8 row_shr:4 row_mask:0xf bank_mask:0xf
	v_mul_f32_dpp v10, v10, v10 row_shr:4 row_mask:0xf bank_mask:0xf
	v_mul_f32_dpp v12, v12, v12 row_shr:4 row_mask:0xf bank_mask:0xf
	v_mul_f32_dpp v14, v14, v14 row_shr:4 row_mask:0xf bank_mask:0xf
	v_mul_f32_dpp v1, v17, v0 row_shr:8 row_mask:0xf bank_mask:0xf bound_ctrl:1
	v_mul_f32_dpp v3, v19, v2 row_shr:8 row_mask:0xf bank_mask:0xf bound_ctrl:1
	v_mul_f32_dpp v5, v21, v4 row_shr:8 row_mask:0xf bank_mask:0xf bound_ctrl:1
	v_mul_f32_dpp v7, v23, v6 row_shr:8 row_mask:0xf bank_mask:0xf bound_ctrl:1
	v_mul_f32_dpp v9, v25, v8 row_shr:8 row_mask:0xf bank_mask:0xf bound_ctrl:1
	v_mul_f32_dpp v11, v27, v10 row_shr:8 row_mask:0xf bank_mask:0xf bound_ctrl:1
	v_mul_f32_dpp v13, v31, v12 row_shr:8 row_mask:0xf bank_mask:0xf bound_ctrl:1
	v_mul_f32_dpp v15, v205, v14 row_shr:8 row_mask:0xf bank_mask:0xf bound_ctrl:1
	v_mul_f32_dpp v0, v0, v0 row_shr:8 row_mask:0xf bank_mask:0xf
	v_mul_f32_dpp v2, v2, v2 row_shr:8 row_mask:0xf bank_mask:0xf
	v_mul_f32_dpp v4, v4, v4 row_shr:8 row_mask:0xf bank_mask:0xf
	v_mul_f32_dpp v6, v6, v6 row_shr:8 row_mask:0xf bank_mask:0xf
	v_mul_f32_dpp v8, v8, v8 row_shr:8 row_mask:0xf bank_mask:0xf
	v_mul_f32_dpp v10, v10, v10 row_shr:8 row_mask:0xf bank_mask:0xf
	v_mul_f32_dpp v12, v12, v12 row_shr:8 row_mask:0xf bank_mask:0xf
	v_mul_f32_dpp v14, v14, v14 row_shr:8 row_mask:0xf bank_mask:0xf
	v_add_f32_e32 v17, v1, v17
	v_add_f32_e32 v19, v3, v19
	v_add_f32_e32 v21, v5, v21
	v_add_f32_e32 v23, v7, v23
	v_add_f32_e32 v25, v9, v25
	v_add_f32_e32 v27, v11, v27
	v_add_f32_e32 v31, v13, v31
	v_add_f32_e32 v205, v15, v205
	v_mov_b32_e32 v93, 1.0
	v_mov_b32_e32 v95, 1.0
	v_mov_b32_e32 v149, 1.0
	v_mov_b32_e32 v151, 1.0
	v_mov_b32_e32 v153, 1.0
	v_mov_b32_e32 v155, 1.0
	v_mov_b32_e32 v201, 1.0
	v_mov_b32_e32 v203, 1.0
	v_lshlrev_b32_e32 v1, 6, v237
	v_cmp_eq_u32_e64 s[8:9], 15, v239
	v_mov_b32_dpp v93, v0 row_shr:1 row_mask:0xf bank_mask:0xf
	v_mov_b32_dpp v92, v17 row_shr:1 row_mask:0xf bank_mask:0xf bound_ctrl:1
	v_mov_b32_dpp v95, v2 row_shr:1 row_mask:0xf bank_mask:0xf
	v_mov_b32_dpp v94, v19 row_shr:1 row_mask:0xf bank_mask:0xf bound_ctrl:1
	v_mov_b32_dpp v149, v4 row_shr:1 row_mask:0xf bank_mask:0xf
	v_mov_b32_dpp v148, v21 row_shr:1 row_mask:0xf bank_mask:0xf bound_ctrl:1
	v_mov_b32_dpp v151, v6 row_shr:1 row_mask:0xf bank_mask:0xf
	v_mov_b32_dpp v150, v23 row_shr:1 row_mask:0xf bank_mask:0xf bound_ctrl:1
	v_mov_b32_dpp v153, v8 row_shr:1 row_mask:0xf bank_mask:0xf
	v_mov_b32_dpp v152, v25 row_shr:1 row_mask:0xf bank_mask:0xf bound_ctrl:1
	v_mov_b32_dpp v155, v10 row_shr:1 row_mask:0xf bank_mask:0xf
	v_mov_b32_dpp v154, v27 row_shr:1 row_mask:0xf bank_mask:0xf bound_ctrl:1
	v_mov_b32_dpp v201, v12 row_shr:1 row_mask:0xf bank_mask:0xf
	v_mov_b32_dpp v200, v31 row_shr:1 row_mask:0xf bank_mask:0xf bound_ctrl:1
	v_mov_b32_dpp v203, v14 row_shr:1 row_mask:0xf bank_mask:0xf
	v_mov_b32_dpp v202, v205 row_shr:1 row_mask:0xf bank_mask:0xf bound_ctrl:1
	s_and_b64 s[20:21], s[46:47], s[8:9]
	v_add_u32_e32 v171, s17, v1
	s_and_saveexec_b64 s[6:7], s[20:21]
	s_cbranch_execz .LBB0_466
	v_mov_b32_e32 v1, v17
	v_mov_b32_e32 v3, v19
	v_mov_b32_e32 v5, v21
	v_mov_b32_e32 v7, v23
	v_mov_b32_e32 v9, v25
	v_mov_b32_e32 v11, v27
	v_mov_b32_e32 v13, v31
	v_mov_b32_e32 v15, v205
	ds_write_b128 v171, v[0:3]
	ds_write_b128 v171, v[4:7] offset:16
	ds_write_b128 v171, v[8:11] offset:32
	ds_write_b128 v171, v[12:15] offset:48
